# previous (v057) plus generic K-loop LDS-DMA loads converted to the saddr form (SGPR base + 32-bit VGPR offset): sixteen 64-bit VALU address adds per K-iteration removed
# speedup vs baseline: 1.0059x; 1.0059x over previous
; #define PG8_STAGE(bufoff, gbase, voff) do { _Pragma("unroll") for (int _i = 0; _i < 2; ++_i) \
;         __builtin_amdgcn_global_load_lds((const unsigned*)((const char*)(gbase) + (voff)[_i]), (PG8_LAS unsigned*)(lds + (bufoff) + ldsw + _i * 8192), 16, 0, 0); } while (0)
; #define PG8_LDA(dst, b, h) do { _Pragma("unroll") for (int m = 0; m < 4; ++m) _Pragma("unroll") for (int k = 0; k < 2; ++k) dst[m][k] = *(const PG8_LAS bf16x8*)(lds + PG8_SA(b, h) + aoff + m * 2048 + k * 1024); } while (0)
; #define PG8_LDB(dst, b, h) do { _Pragma("unroll") for (int n = 0; n < 2; ++n) _Pragma("unroll") for (int k = 0; k < 2; ++k) dst[n][k] = *(const PG8_LAS bf16x8*)(lds + PG8_SB(b, h) + boff + n * 2048 + k * 1024); } while (0)
; #define PG8_MMA(ai, bj, At, Bt) do { __builtin_amdgcn_s_setprio(1); _Pragma("unroll") for (int m = 0; m < 4; ++m) _Pragma("unroll") for (int n = 0; n < 2; ++n) _Pragma("unroll") for (int k = 0; k < 2; ++k) \
;         acc[ai][bj][m][n] = __builtin_amdgcn_mfma_f32_16x16x32_bf16(Bt[n][k], At[m][k], acc[ai][bj][m][n], 0, 0, 0); __builtin_amdgcn_s_setprio(0); } while (0)
; #define PG8_WAIT_V(n) asm volatile("s_waitcnt vmcnt(" #n ")" ::: "memory")
; #define PG8_WAIT_L(n) asm volatile("s_waitcnt lgkmcnt(" #n ")" ::: "memory")
; #define PG8_BAR __builtin_amdgcn_s_barrier()
; #define PG8_SCHED __builtin_amdgcn_sched_barrier(0)
; template <class Epi, class Sched, bool ALIGN_EPI = false>
; __device__ __forceinline__ void gemm_phase(PG8_LAS unsigned char* lds, const Gemm g, const Sched& S, const Epi& E, int tid_in) {
;     ...
;             PG8_LDB(B0, 0, 0); PG8_LDB(B1, 0, 1); PG8_SCHED; PG8_LDA(At, 0, 0); PG8_STAGE(PG8_SA(1, 1), a1 + hstepA, voffA);
;             PG8_WAIT_V(8); PG8_WAIT_L(0); PG8_BAR; PG8_MMA(0, 0, At, B0); PG8_MMA(0, 1, At, B1); PG8_BAR; PG8_SCHED;
;             PG8_LDA(At, 0, 1); PG8_STAGE(PG8_SB(0, 0), b2, voffB); PG8_STAGE(PG8_SB(0, 1), b2 + hstepB, voffB); PG8_STAGE(PG8_SA(0, 0), a2, voffA);
;             PG8_WAIT_V(8); PG8_WAIT_L(0); PG8_BAR; PG8_MMA(1, 0, At, B0); PG8_MMA(1, 1, At, B1); PG8_BAR; PG8_SCHED;
.LBB0_267:
	s_add_i32 s63, s58, 2
	s_add_u32 s22, s60, 0x80
	s_addc_u32 s23, s61, 0
	s_add_i32 s89, 0, 0x10000
	s_cmp_eq_u32 s77, s58
	s_cselect_b32 s59, s19, s23
	s_cselect_b32 s58, s18, s22
	v_add_u32_e32 v80, s89, v245
	s_cselect_b32 s23, s35, s62
	s_cselect_b32 s22, s34, s57
	s_add_i32 s90, 0, 0x14000
	ds_read_b128 v[130:133], v80
	ds_read_b128 v[134:137], v80 offset:1024
	ds_read_b128 v[138:141], v80 offset:2048
	ds_read_b128 v[142:145], v80 offset:3072
	v_add_u32_e32 v80, s90, v245
	ds_read_b128 v[146:149], v80
	ds_read_b128 v[150:153], v80 offset:1024
	ds_read_b128 v[154:157], v80 offset:2048
	ds_read_b128 v[158:161], v80 offset:3072
	s_mov_b32 m0, s74
	ds_read_b128 v[162:165], v248
	ds_read_b128 v[166:169], v248 offset:1024
	ds_read_b128 v[170:173], v248 offset:2048
	ds_read_b128 v[174:177], v248 offset:3072
	ds_read_b128 v[178:181], v248 offset:4096
	ds_read_b128 v[198:201], v248 offset:5120
	ds_read_b128 v[202:205], v248 offset:6144
	ds_read_b128 v[206:209], v248 offset:7168
	global_load_lds_dwordx4 v184, s[60:61]
	s_mov_b32 m0, s75
	s_nop 0
	global_load_lds_dwordx4 v188, s[60:61]
	s_add_i32 m0, s70, 0xc000
	s_nop 0
	global_load_lds_dwordx4 v194, s[60:61]
	s_add_i32 m0, s70, 0xe000
	s_nop 0
	global_load_lds_dwordx4 v196, s[60:61]
	s_waitcnt vmcnt(8)
	s_waitcnt lgkmcnt(0)
	v_mfma_f32_16x16x32_bf16 v[4:7], v[130:133], v[162:165], v[4:7]
	v_mfma_f32_16x16x32_bf16 v[0:3], v[138:141], v[162:165], v[0:3]
	s_barrier
	s_setprio 1
	s_waitcnt lgkmcnt(0)
	v_mfma_f32_16x16x32_bf16 v[20:23], v[130:133], v[170:173], v[20:23]
	v_mfma_f32_16x16x32_bf16 v[16:19], v[138:141], v[170:173], v[16:19]
	v_mfma_f32_16x16x32_bf16 v[36:39], v[130:133], v[178:181], v[36:39]
	v_mfma_f32_16x16x32_bf16 v[32:35], v[138:141], v[178:181], v[32:35]
	v_mfma_f32_16x16x32_bf16 v[52:55], v[130:133], v[202:205], v[52:55]
	v_mfma_f32_16x16x32_bf16 v[48:51], v[138:141], v[202:205], v[48:51]
	v_mfma_f32_16x16x32_bf16 v[4:7], v[134:137], v[166:169], v[4:7]
	v_mfma_f32_16x16x32_bf16 v[0:3], v[142:145], v[166:169], v[0:3]
	v_mfma_f32_16x16x32_bf16 v[20:23], v[134:137], v[174:177], v[20:23]
	v_mfma_f32_16x16x32_bf16 v[16:19], v[142:145], v[174:177], v[16:19]
	v_mfma_f32_16x16x32_bf16 v[36:39], v[134:137], v[198:201], v[36:39]
	v_mfma_f32_16x16x32_bf16 v[32:35], v[142:145], v[198:201], v[32:35]
	v_mfma_f32_16x16x32_bf16 v[52:55], v[134:137], v[206:209], v[52:55]
	v_mfma_f32_16x16x32_bf16 v[48:51], v[142:145], v[206:209], v[48:51]
	s_setprio 0
	s_setprio 1
	v_mfma_f32_16x16x32_bf16 v[12:15], v[146:149], v[162:165], v[12:15]
	v_mfma_f32_16x16x32_bf16 v[8:11], v[154:157], v[162:165], v[8:11]
	v_mfma_f32_16x16x32_bf16 v[28:31], v[146:149], v[170:173], v[28:31]
	v_mfma_f32_16x16x32_bf16 v[24:27], v[154:157], v[170:173], v[24:27]
	v_mfma_f32_16x16x32_bf16 v[44:47], v[146:149], v[178:181], v[44:47]
	v_mfma_f32_16x16x32_bf16 v[40:43], v[154:157], v[178:181], v[40:43]
	v_mfma_f32_16x16x32_bf16 v[60:63], v[146:149], v[202:205], v[60:63]
	v_mfma_f32_16x16x32_bf16 v[56:59], v[154:157], v[202:205], v[56:59]
	v_mfma_f32_16x16x32_bf16 v[12:15], v[150:153], v[166:169], v[12:15]
	v_mfma_f32_16x16x32_bf16 v[8:11], v[158:161], v[166:169], v[8:11]
	v_mfma_f32_16x16x32_bf16 v[28:31], v[150:153], v[174:177], v[28:31]
	v_mfma_f32_16x16x32_bf16 v[24:27], v[158:161], v[174:177], v[24:27]
	v_mfma_f32_16x16x32_bf16 v[44:47], v[150:153], v[198:201], v[44:47]
	v_mfma_f32_16x16x32_bf16 v[40:43], v[158:161], v[198:201], v[40:43]
	v_mfma_f32_16x16x32_bf16 v[60:63], v[150:153], v[206:209], v[60:63]
	v_mfma_f32_16x16x32_bf16 v[56:59], v[158:161], v[206:209], v[56:59]
	s_setprio 0
	s_barrier
	s_add_i32 s89, s89, s69
	s_mov_b64 vcc, s[22:23]
	s_mov_b32 m0, s89
	ds_read_b128 v[162:165], v248 offset:16384
	ds_read_b128 v[166:169], v248 offset:17408
	ds_read_b128 v[170:173], v248 offset:18432
	ds_read_b128 v[174:177], v248 offset:19456
	ds_read_b128 v[178:181], v248 offset:20480
	ds_read_b128 v[198:201], v248 offset:21504
	ds_read_b128 v[202:205], v248 offset:22528
	ds_read_b128 v[206:209], v248 offset:23552
	global_load_lds_dwordx4 v186, s[22:23]
	s_add_i32 m0, s89, 0x2000
	s_add_u32 s22, s22, s33
	s_addc_u32 s23, s23, 0
	s_add_i32 s89, s90, s69
	global_load_lds_dwordx4 v190, vcc
	s_mov_b32 m0, s89
	s_nop 0
	global_load_lds_dwordx4 v186, s[22:23]
	s_add_i32 m0, s89, 0x2000
	s_nop 0
	global_load_lds_dwordx4 v190, s[22:23]
	s_waitcnt vmcnt(6)
	s_waitcnt lgkmcnt(0)
	v_mfma_f32_16x16x32_bf16 v[64:67], v[130:133], v[162:165], v[64:67]
	v_mfma_f32_16x16x32_bf16 v[68:71], v[138:141], v[162:165], v[68:71]
	s_barrier
	s_setprio 1
	s_waitcnt lgkmcnt(0)
	v_mfma_f32_16x16x32_bf16 v[82:85], v[130:133], v[170:173], v[82:85]
	v_mfma_f32_16x16x32_bf16 v[86:89], v[138:141], v[170:173], v[86:89]
	v_mfma_f32_16x16x32_bf16 v[98:101], v[130:133], v[178:181], v[98:101]
	v_mfma_f32_16x16x32_bf16 v[102:105], v[138:141], v[178:181], v[102:105]
	v_mfma_f32_16x16x32_bf16 v[114:117], v[130:133], v[202:205], v[114:117]
	v_mfma_f32_16x16x32_bf16 v[118:121], v[138:141], v[202:205], v[118:121]
	v_mfma_f32_16x16x32_bf16 v[64:67], v[134:137], v[166:169], v[64:67]
	v_mfma_f32_16x16x32_bf16 v[68:71], v[142:145], v[166:169], v[68:71]
	v_mfma_f32_16x16x32_bf16 v[82:85], v[134:137], v[174:177], v[82:85]
	v_mfma_f32_16x16x32_bf16 v[86:89], v[142:145], v[174:177], v[86:89]
	v_mfma_f32_16x16x32_bf16 v[98:101], v[134:137], v[198:201], v[98:101]
	v_mfma_f32_16x16x32_bf16 v[102:105], v[142:145], v[198:201], v[102:105]
	v_mfma_f32_16x16x32_bf16 v[114:117], v[134:137], v[206:209], v[114:117]
	v_mfma_f32_16x16x32_bf16 v[118:121], v[142:145], v[206:209], v[118:121]
	s_setprio 0
	s_setprio 1
	v_mfma_f32_16x16x32_bf16 v[76:79], v[146:149], v[162:165], v[76:79]
	v_mfma_f32_16x16x32_bf16 v[72:75], v[154:157], v[162:165], v[72:75]
	v_mfma_f32_16x16x32_bf16 v[94:97], v[146:149], v[170:173], v[94:97]
	v_mfma_f32_16x16x32_bf16 v[90:93], v[154:157], v[170:173], v[90:93]
	v_mfma_f32_16x16x32_bf16 v[110:113], v[146:149], v[178:181], v[110:113]
	v_mfma_f32_16x16x32_bf16 v[106:109], v[154:157], v[178:181], v[106:109]
	v_mfma_f32_16x16x32_bf16 v[126:129], v[146:149], v[202:205], v[126:129]
	v_mfma_f32_16x16x32_bf16 v[122:125], v[154:157], v[202:205], v[122:125]
	v_mfma_f32_16x16x32_bf16 v[76:79], v[150:153], v[166:169], v[76:79]
	v_mfma_f32_16x16x32_bf16 v[72:75], v[158:161], v[166:169], v[72:75]
	v_mfma_f32_16x16x32_bf16 v[94:97], v[150:153], v[174:177], v[94:97]
	v_mfma_f32_16x16x32_bf16 v[90:93], v[158:161], v[174:177], v[90:93]
	v_mfma_f32_16x16x32_bf16 v[110:113], v[150:153], v[198:201], v[110:113]
	v_mfma_f32_16x16x32_bf16 v[106:109], v[158:161], v[198:201], v[106:109]
	v_mfma_f32_16x16x32_bf16 v[126:129], v[150:153], v[206:209], v[126:129]
	v_mfma_f32_16x16x32_bf16 v[122:125], v[158:161], v[206:209], v[122:125]
	s_setprio 0
	s_barrier
; #define PG8_STAGE(bufoff, gbase, voff) do { _Pragma("unroll") for (int _i = 0; _i < 2; ++_i) \
;         __builtin_amdgcn_global_load_lds((const unsigned*)((const char*)(gbase) + (voff)[_i]), (PG8_LAS unsigned*)(lds + (bufoff) + ldsw + _i * 8192), 16, 0, 0); } while (0)
; #define PG8_LDA(dst, b, h) do { _Pragma("unroll") for (int m = 0; m < 4; ++m) _Pragma("unroll") for (int k = 0; k < 2; ++k) dst[m][k] = *(const PG8_LAS bf16x8*)(lds + PG8_SA(b, h) + aoff + m * 2048 + k * 1024); } while (0)
; #define PG8_LDB(dst, b, h) do { _Pragma("unroll") for (int n = 0; n < 2; ++n) _Pragma("unroll") for (int k = 0; k < 2; ++k) dst[n][k] = *(const PG8_LAS bf16x8*)(lds + PG8_SB(b, h) + boff + n * 2048 + k * 1024); } while (0)
; #define PG8_MMA(ai, bj, At, Bt) do { __builtin_amdgcn_s_setprio(1); _Pragma("unroll") for (int m = 0; m < 4; ++m) _Pragma("unroll") for (int n = 0; n < 2; ++n) _Pragma("unroll") for (int k = 0; k < 2; ++k) \
;         acc[ai][bj][m][n] = __builtin_amdgcn_mfma_f32_16x16x32_bf16(Bt[n][k], At[m][k], acc[ai][bj][m][n], 0, 0, 0); __builtin_amdgcn_s_setprio(0); } while (0)
; #define PG8_WAIT_V(n) asm volatile("s_waitcnt vmcnt(" #n ")" ::: "memory")
; #define PG8_WAIT_L(n) asm volatile("s_waitcnt lgkmcnt(" #n ")" ::: "memory")
; #define PG8_BAR __builtin_amdgcn_s_barrier()
; #define PG8_SCHED __builtin_amdgcn_sched_barrier(0)
; template <class Epi, class Sched, bool ALIGN_EPI = false>
; __device__ __forceinline__ void gemm_phase(PG8_LAS unsigned char* lds, const Gemm g, const Sched& S, const Epi& E, int tid_in) {
;     ...
;             PG8_LDB(B0, 1, 0); PG8_LDB(B1, 1, 1); PG8_SCHED; PG8_LDA(At, 1, 0); PG8_STAGE(PG8_SA(0, 1), a2 + hstepA, voffA);
;             PG8_WAIT_V(8); PG8_WAIT_L(0); PG8_BAR; PG8_MMA(0, 0, At, B0); PG8_MMA(0, 1, At, B1); PG8_BAR; PG8_SCHED;
;             PG8_LDA(At, 1, 1); PG8_STAGE(PG8_SB(1, 0), b3, voffB); PG8_STAGE(PG8_SB(1, 1), b3 + hstepB, voffB); PG8_STAGE(PG8_SA(1, 0), a3, voffA);
;             PG8_WAIT_V(8); PG8_WAIT_L(0); PG8_BAR; PG8_MMA(1, 0, At, B0); PG8_MMA(1, 1, At, B1); PG8_BAR; PG8_SCHED;
;         }
	s_add_i32 s89, 0, 0x18000
	v_add_u32_e32 v80, s89, v245
	s_add_i32 s90, 0, 0x1c000
	ds_read_b128 v[130:133], v80
	ds_read_b128 v[134:137], v80 offset:1024
	ds_read_b128 v[138:141], v80 offset:2048
	ds_read_b128 v[142:145], v80 offset:3072
	v_add_u32_e32 v80, s90, v245
	ds_read_b128 v[146:149], v80
	ds_read_b128 v[150:153], v80 offset:1024
	ds_read_b128 v[154:157], v80 offset:2048
	ds_read_b128 v[158:161], v80 offset:3072
	s_add_u32 s22, s58, s0
	s_addc_u32 s23, s59, 0
	s_mov_b32 m0, s70
	ds_read_b128 v[162:165], v248 offset:32768
	ds_read_b128 v[166:169], v248 offset:33792
	ds_read_b128 v[170:173], v248 offset:34816
	ds_read_b128 v[174:177], v248 offset:35840
	ds_read_b128 v[178:181], v248 offset:36864
	ds_read_b128 v[198:201], v248 offset:37888
	ds_read_b128 v[202:205], v248 offset:38912
	ds_read_b128 v[206:209], v248 offset:39936
	global_load_lds_dwordx4 v184, s[58:59]
	s_mov_b32 m0, s71
	s_nop 0
	global_load_lds_dwordx4 v188, s[58:59]
	s_mov_b32 m0, s72
	s_nop 0
	global_load_lds_dwordx4 v184, s[22:23]
	s_mov_b32 m0, s73
	s_nop 0
	global_load_lds_dwordx4 v188, s[22:23]
	s_waitcnt vmcnt(8)
	s_waitcnt lgkmcnt(0)
	v_mfma_f32_16x16x32_bf16 v[4:7], v[130:133], v[162:165], v[4:7]
	v_mfma_f32_16x16x32_bf16 v[0:3], v[138:141], v[162:165], v[0:3]
	s_barrier
	s_setprio 1
	s_waitcnt lgkmcnt(0)
	v_mfma_f32_16x16x32_bf16 v[20:23], v[130:133], v[170:173], v[20:23]
	v_mfma_f32_16x16x32_bf16 v[16:19], v[138:141], v[170:173], v[16:19]
	v_mfma_f32_16x16x32_bf16 v[36:39], v[130:133], v[178:181], v[36:39]
	v_mfma_f32_16x16x32_bf16 v[32:35], v[138:141], v[178:181], v[32:35]
	v_mfma_f32_16x16x32_bf16 v[52:55], v[130:133], v[202:205], v[52:55]
	v_mfma_f32_16x16x32_bf16 v[48:51], v[138:141], v[202:205], v[48:51]
	v_mfma_f32_16x16x32_bf16 v[4:7], v[134:137], v[166:169], v[4:7]
	v_mfma_f32_16x16x32_bf16 v[0:3], v[142:145], v[166:169], v[0:3]
	v_mfma_f32_16x16x32_bf16 v[20:23], v[134:137], v[174:177], v[20:23]
	v_mfma_f32_16x16x32_bf16 v[16:19], v[142:145], v[174:177], v[16:19]
	v_mfma_f32_16x16x32_bf16 v[36:39], v[134:137], v[198:201], v[36:39]
	v_mfma_f32_16x16x32_bf16 v[32:35], v[142:145], v[198:201], v[32:35]
	v_mfma_f32_16x16x32_bf16 v[52:55], v[134:137], v[206:209], v[52:55]
	v_mfma_f32_16x16x32_bf16 v[48:51], v[142:145], v[206:209], v[48:51]
	s_setprio 0
	s_setprio 1
	v_mfma_f32_16x16x32_bf16 v[12:15], v[146:149], v[162:165], v[12:15]
	v_mfma_f32_16x16x32_bf16 v[8:11], v[154:157], v[162:165], v[8:11]
	v_mfma_f32_16x16x32_bf16 v[28:31], v[146:149], v[170:173], v[28:31]
	v_mfma_f32_16x16x32_bf16 v[24:27], v[154:157], v[170:173], v[24:27]
	v_mfma_f32_16x16x32_bf16 v[44:47], v[146:149], v[178:181], v[44:47]
	v_mfma_f32_16x16x32_bf16 v[40:43], v[154:157], v[178:181], v[40:43]
	v_mfma_f32_16x16x32_bf16 v[60:63], v[146:149], v[202:205], v[60:63]
	v_mfma_f32_16x16x32_bf16 v[56:59], v[154:157], v[202:205], v[56:59]
	v_mfma_f32_16x16x32_bf16 v[12:15], v[150:153], v[166:169], v[12:15]
	v_mfma_f32_16x16x32_bf16 v[8:11], v[158:161], v[166:169], v[8:11]
	v_mfma_f32_16x16x32_bf16 v[28:31], v[150:153], v[174:177], v[28:31]
	v_mfma_f32_16x16x32_bf16 v[24:27], v[158:161], v[174:177], v[24:27]
	v_mfma_f32_16x16x32_bf16 v[44:47], v[150:153], v[198:201], v[44:47]
	v_mfma_f32_16x16x32_bf16 v[40:43], v[158:161], v[198:201], v[40:43]
	v_mfma_f32_16x16x32_bf16 v[60:63], v[150:153], v[206:209], v[60:63]
	v_mfma_f32_16x16x32_bf16 v[56:59], v[158:161], v[206:209], v[56:59]
	s_setprio 0
	s_barrier
	s_add_i32 s22, s89, s69
	s_add_u32 vcc_lo, vcc_lo, 0x80
	s_addc_u32 vcc_hi, vcc_hi, 0
	s_mov_b32 m0, s22
	ds_read_b128 v[162:165], v248 offset:49152
	ds_read_b128 v[166:169], v248 offset:50176
	ds_read_b128 v[170:173], v248 offset:51200
	ds_read_b128 v[174:177], v248 offset:52224
	ds_read_b128 v[178:181], v248 offset:53248
	ds_read_b128 v[198:201], v248 offset:54272
	ds_read_b128 v[202:205], v248 offset:55296
	ds_read_b128 v[206:209], v248 offset:56320
	global_load_lds_dwordx4 v186, vcc
	s_add_i32 m0, s22, 0x2000
	s_add_i32 s22, s90, s69
	global_load_lds_dwordx4 v190, vcc
	s_add_u32 vcc_lo, vcc_lo, s33
	s_addc_u32 vcc_hi, vcc_hi, 0
	s_mov_b32 m0, s22
	s_nop 0
	global_load_lds_dwordx4 v186, vcc
	s_add_i32 m0, s22, 0x2000
	s_nop 0
	global_load_lds_dwordx4 v190, vcc
	s_waitcnt vmcnt(6)
	s_waitcnt lgkmcnt(0)
	v_mfma_f32_16x16x32_bf16 v[64:67], v[130:133], v[162:165], v[64:67]
	v_mfma_f32_16x16x32_bf16 v[68:71], v[138:141], v[162:165], v[68:71]
	s_barrier
	s_setprio 1
	s_waitcnt lgkmcnt(0)
	v_mfma_f32_16x16x32_bf16 v[82:85], v[130:133], v[170:173], v[82:85]
	v_mfma_f32_16x16x32_bf16 v[86:89], v[138:141], v[170:173], v[86:89]
	v_mfma_f32_16x16x32_bf16 v[98:101], v[130:133], v[178:181], v[98:101]
	v_mfma_f32_16x16x32_bf16 v[102:105], v[138:141], v[178:181], v[102:105]
	v_mfma_f32_16x16x32_bf16 v[114:117], v[130:133], v[202:205], v[114:117]
	v_mfma_f32_16x16x32_bf16 v[118:121], v[138:141], v[202:205], v[118:121]
	v_mfma_f32_16x16x32_bf16 v[64:67], v[134:137], v[166:169], v[64:67]
	v_mfma_f32_16x16x32_bf16 v[68:71], v[142:145], v[166:169], v[68:71]
	v_mfma_f32_16x16x32_bf16 v[82:85], v[134:137], v[174:177], v[82:85]
	v_mfma_f32_16x16x32_bf16 v[86:89], v[142:145], v[174:177], v[86:89]
	v_mfma_f32_16x16x32_bf16 v[98:101], v[134:137], v[198:201], v[98:101]
	v_mfma_f32_16x16x32_bf16 v[102:105], v[142:145], v[198:201], v[102:105]
	v_mfma_f32_16x16x32_bf16 v[114:117], v[134:137], v[206:209], v[114:117]
	v_mfma_f32_16x16x32_bf16 v[118:121], v[142:145], v[206:209], v[118:121]
	s_setprio 0
	s_setprio 1
	v_mfma_f32_16x16x32_bf16 v[76:79], v[146:149], v[162:165], v[76:79]
	v_mfma_f32_16x16x32_bf16 v[72:75], v[154:157], v[162:165], v[72:75]
	v_mfma_f32_16x16x32_bf16 v[94:97], v[146:149], v[170:173], v[94:97]
	v_mfma_f32_16x16x32_bf16 v[90:93], v[154:157], v[170:173], v[90:93]
	v_mfma_f32_16x16x32_bf16 v[110:113], v[146:149], v[178:181], v[110:113]
	v_mfma_f32_16x16x32_bf16 v[106:109], v[154:157], v[178:181], v[106:109]
	v_mfma_f32_16x16x32_bf16 v[126:129], v[146:149], v[202:205], v[126:129]
	v_mfma_f32_16x16x32_bf16 v[122:125], v[154:157], v[202:205], v[122:125]
	v_mfma_f32_16x16x32_bf16 v[76:79], v[150:153], v[166:169], v[76:79]
	v_mfma_f32_16x16x32_bf16 v[72:75], v[158:161], v[166:169], v[72:75]
	v_mfma_f32_16x16x32_bf16 v[94:97], v[150:153], v[174:177], v[94:97]
	v_mfma_f32_16x16x32_bf16 v[90:93], v[158:161], v[174:177], v[90:93]
	v_mfma_f32_16x16x32_bf16 v[110:113], v[150:153], v[198:201], v[110:113]
	v_mfma_f32_16x16x32_bf16 v[106:109], v[158:161], v[198:201], v[106:109]
	v_mfma_f32_16x16x32_bf16 v[126:129], v[150:153], v[206:209], v[126:129]
	v_mfma_f32_16x16x32_bf16 v[122:125], v[158:161], v[206:209], v[122:125]
	s_setprio 0
	s_barrier
	s_add_u32 s60, s60, 0x100
	s_addc_u32 s61, s61, 0
	s_add_u32 s57, s57, 0x100
	s_addc_u32 s62, s62, 0
	s_cmp_ge_u32 s63, s76
	s_mov_b32 s58, s63
	s_cbranch_scc0 .LBB0_267
	s_and_b64 vcc, exec, s[14:15]
	s_cbranch_vccnz .LBB0_271
	s_cmp_lt_i32 s64, 3
	s_mov_b64 s[58:59], -1
	s_cbranch_scc0 .LBB0_272
